# phase 0 transposes: nt (streaming) hint on the read-once f32 weight loads and the write-once bf16 stores
# speedup vs baseline: 1.0019x; 1.0019x over previous
.Lp0_fl_a:
	global_load_dword v150, v141, s[88:89] nt
	s_add_u32 s88, s88, s90
	s_addc_u32 s89, s89, 0
	global_load_dword v151, v141, s[88:89] nt
	s_add_u32 s88, s88, s90
	s_addc_u32 s89, s89, 0
	global_load_dword v152, v141, s[88:89] nt
	s_add_u32 s88, s88, s90
	s_addc_u32 s89, s89, 0
	global_load_dword v153, v141, s[88:89] nt
	s_add_u32 s88, s88, s90
	s_addc_u32 s89, s89, 0
	global_load_dword v154, v141, s[88:89] nt
	s_add_u32 s88, s88, s90
	s_addc_u32 s89, s89, 0
	global_load_dword v155, v141, s[88:89] nt
	s_add_u32 s88, s88, s90
	s_addc_u32 s89, s89, 0
	global_load_dword v156, v141, s[88:89] nt
	s_add_u32 s88, s88, s90
	s_addc_u32 s89, s89, 0
	global_load_dword v157, v141, s[88:89] nt
	s_add_u32 s88, s88, s90
	s_addc_u32 s89, s89, 0
	global_load_dword v158, v141, s[88:89] nt
	s_add_u32 s88, s88, s90
	s_addc_u32 s89, s89, 0
	global_load_dword v159, v141, s[88:89] nt
	s_add_u32 s88, s88, s90
	s_addc_u32 s89, s89, 0
	global_load_dword v160, v141, s[88:89] nt
	s_add_u32 s88, s88, s90
	s_addc_u32 s89, s89, 0
	global_load_dword v161, v141, s[88:89] nt
	s_add_u32 s88, s88, s90
	s_addc_u32 s89, s89, 0
	global_load_dword v162, v141, s[88:89] nt
	s_add_u32 s88, s88, s90
	s_addc_u32 s89, s89, 0
	global_load_dword v163, v141, s[88:89] nt
	s_add_u32 s88, s88, s90
	s_addc_u32 s89, s89, 0
	global_load_dword v164, v141, s[88:89] nt
	s_add_u32 s88, s88, s90
	s_addc_u32 s89, s89, 0
	global_load_dword v165, v141, s[88:89] nt
	s_add_u32 s88, s88, s90
	s_addc_u32 s89, s89, 0
	global_load_dword v166, v141, s[88:89] nt
	s_add_u32 s88, s88, s90
	s_addc_u32 s89, s89, 0
	global_load_dword v167, v141, s[88:89] nt
	s_add_u32 s88, s88, s90
	s_addc_u32 s89, s89, 0
	global_load_dword v168, v141, s[88:89] nt
	s_add_u32 s88, s88, s90
	s_addc_u32 s89, s89, 0
	global_load_dword v169, v141, s[88:89] nt
	s_add_u32 s88, s88, s90
	s_addc_u32 s89, s89, 0
	global_load_dword v170, v141, s[88:89] nt
	s_add_u32 s88, s88, s90
	s_addc_u32 s89, s89, 0
	global_load_dword v171, v141, s[88:89] nt
	s_add_u32 s88, s88, s90
	s_addc_u32 s89, s89, 0
	global_load_dword v172, v141, s[88:89] nt
	s_add_u32 s88, s88, s90
	s_addc_u32 s89, s89, 0
	global_load_dword v173, v141, s[88:89] nt
	s_add_u32 s88, s88, s90
	s_addc_u32 s89, s89, 0
	global_load_dword v174, v141, s[88:89] nt
	s_add_u32 s88, s88, s90
	s_addc_u32 s89, s89, 0
	global_load_dword v175, v141, s[88:89] nt
	s_add_u32 s88, s88, s90
	s_addc_u32 s89, s89, 0
	global_load_dword v176, v141, s[88:89] nt
	s_add_u32 s88, s88, s90
	s_addc_u32 s89, s89, 0
	global_load_dword v177, v141, s[88:89] nt
	s_add_u32 s88, s88, s90
	s_addc_u32 s89, s89, 0
	global_load_dword v178, v141, s[88:89] nt
	s_add_u32 s88, s88, s90
	s_addc_u32 s89, s89, 0
	global_load_dword v179, v141, s[88:89] nt
	s_add_u32 s88, s88, s90
	s_addc_u32 s89, s89, 0
	global_load_dword v180, v141, s[88:89] nt
	s_add_u32 s88, s88, s90
	s_addc_u32 s89, s89, 0
	global_load_dword v181, v141, s[88:89] nt
	s_mov_b64 exec, -1
	s_lshl_b32 s95, s87, 1
	s_add_u32 s92, s78, s95
	s_addc_u32 s93, s79, 0
	s_mov_b32 s94, s91
	s_lshl_b32 s96, s80, 1
	v_mov_b32_e32 v142, s83
	s_cmp_eq_u32 s82, 0
	s_cbranch_scc1 .Lp0_r0_a
	s_cmp_eq_u32 s82, 1
	s_cbranch_scc1 .Lp0_r1_a
	s_cmp_lt_u32 s86, 0x1000
	s_cbranch_scc1 .Lp0_r3a_a
	s_cmp_lt_u32 s86, 0x1800
	s_cbranch_scc1 .Lp0_r0_a
	s_cmp_lt_u32 s86, 0x1c00
	s_cbranch_scc1 .Lp0_r3c_a
	s_add_u32 s95, s86, 0
	v_add_u32_e32 v143, s95, v105
	v_add_u32_e32 v200, 0xffffe3f0, v143
	v_and_b32_e32 v201, 32, v200
	v_lshlrev_b32_e32 v201, 2, v201
	v_and_b32_e32 v200, 31, v200
	v_add_u32_e32 v200, 0x1c00, v200
	v_add_u32_e32 v200, v200, v201
	v_mov_b32_e32 v202, 0x1c10
	v_cmp_gt_u32_e32 vcc, v202, v143
	v_add_u32_e32 v201, 32, v143
	s_nop 0
	v_cndmask_b32_e32 v203, v200, v201, vcc
	v_mad_u32_u24 v108, v203, s96, v104
	s_add_u32 s95, s86, 8
	v_add_u32_e32 v143, s95, v105
	v_add_u32_e32 v200, 0xffffe3f0, v143
	v_and_b32_e32 v201, 32, v200
	v_lshlrev_b32_e32 v201, 2, v201
	v_and_b32_e32 v200, 31, v200
	v_add_u32_e32 v200, 0x1c00, v200
	v_add_u32_e32 v200, v200, v201
	v_mov_b32_e32 v202, 0x1c10
	v_cmp_gt_u32_e32 vcc, v202, v143
	v_add_u32_e32 v201, 32, v143
	s_nop 0
	v_cndmask_b32_e32 v203, v200, v201, vcc
	v_mad_u32_u24 v109, v203, s96, v104
	s_add_u32 s95, s86, 16
	v_add_u32_e32 v143, s95, v105
	v_add_u32_e32 v200, 0xffffe3f0, v143
	v_and_b32_e32 v201, 32, v200
	v_lshlrev_b32_e32 v201, 2, v201
	v_and_b32_e32 v200, 31, v200
	v_add_u32_e32 v200, 0x1c00, v200
	v_add_u32_e32 v200, v200, v201
	v_mov_b32_e32 v202, 0x1c10
	v_cmp_gt_u32_e32 vcc, v202, v143
	v_add_u32_e32 v201, 32, v143
	s_nop 0
	v_cndmask_b32_e32 v203, v200, v201, vcc
	v_mad_u32_u24 v110, v203, s96, v104
	s_add_u32 s95, s86, 24
	v_add_u32_e32 v143, s95, v105
	v_add_u32_e32 v200, 0xffffe3f0, v143
	v_and_b32_e32 v201, 32, v200
	v_lshlrev_b32_e32 v201, 2, v201
	v_and_b32_e32 v200, 31, v200
	v_add_u32_e32 v200, 0x1c00, v200
	v_add_u32_e32 v200, v200, v201
	v_mov_b32_e32 v202, 0x1c10
	v_cmp_gt_u32_e32 vcc, v202, v143
	v_add_u32_e32 v201, 32, v143
	s_nop 0
	v_cndmask_b32_e32 v203, v200, v201, vcc
	v_mad_u32_u24 v140, v203, s96, v104
	s_branch .Lp0_rd_a

.Lp0_fl_b:
	global_load_dword v150, v141, s[88:89] nt
	s_add_u32 s88, s88, s90
	s_addc_u32 s89, s89, 0
	global_load_dword v151, v141, s[88:89] nt
	s_add_u32 s88, s88, s90
	s_addc_u32 s89, s89, 0
	global_load_dword v152, v141, s[88:89] nt
	s_add_u32 s88, s88, s90
	s_addc_u32 s89, s89, 0
	global_load_dword v153, v141, s[88:89] nt
	s_add_u32 s88, s88, s90
	s_addc_u32 s89, s89, 0
	global_load_dword v154, v141, s[88:89] nt
	s_add_u32 s88, s88, s90
	s_addc_u32 s89, s89, 0
	global_load_dword v155, v141, s[88:89] nt
	s_add_u32 s88, s88, s90
	s_addc_u32 s89, s89, 0
	global_load_dword v156, v141, s[88:89] nt
	s_add_u32 s88, s88, s90
	s_addc_u32 s89, s89, 0
	global_load_dword v157, v141, s[88:89] nt
	s_add_u32 s88, s88, s90
	s_addc_u32 s89, s89, 0
	global_load_dword v158, v141, s[88:89] nt
	s_add_u32 s88, s88, s90
	s_addc_u32 s89, s89, 0
	global_load_dword v159, v141, s[88:89] nt
	s_add_u32 s88, s88, s90
	s_addc_u32 s89, s89, 0
	global_load_dword v160, v141, s[88:89] nt
	s_add_u32 s88, s88, s90
	s_addc_u32 s89, s89, 0
	global_load_dword v161, v141, s[88:89] nt
	s_add_u32 s88, s88, s90
	s_addc_u32 s89, s89, 0
	global_load_dword v162, v141, s[88:89] nt
	s_add_u32 s88, s88, s90
	s_addc_u32 s89, s89, 0
	global_load_dword v163, v141, s[88:89] nt
	s_add_u32 s88, s88, s90
	s_addc_u32 s89, s89, 0
	global_load_dword v164, v141, s[88:89] nt
	s_add_u32 s88, s88, s90
	s_addc_u32 s89, s89, 0
	global_load_dword v165, v141, s[88:89] nt
	s_add_u32 s88, s88, s90
	s_addc_u32 s89, s89, 0
	global_load_dword v166, v141, s[88:89] nt
	s_add_u32 s88, s88, s90
	s_addc_u32 s89, s89, 0
	global_load_dword v167, v141, s[88:89] nt
	s_add_u32 s88, s88, s90
	s_addc_u32 s89, s89, 0
	global_load_dword v168, v141, s[88:89] nt
	s_add_u32 s88, s88, s90
	s_addc_u32 s89, s89, 0
	global_load_dword v169, v141, s[88:89] nt
	s_add_u32 s88, s88, s90
	s_addc_u32 s89, s89, 0
	global_load_dword v170, v141, s[88:89] nt
	s_add_u32 s88, s88, s90
	s_addc_u32 s89, s89, 0
	global_load_dword v171, v141, s[88:89] nt
	s_add_u32 s88, s88, s90
	s_addc_u32 s89, s89, 0
	global_load_dword v172, v141, s[88:89] nt
	s_add_u32 s88, s88, s90
	s_addc_u32 s89, s89, 0
	global_load_dword v173, v141, s[88:89] nt
	s_add_u32 s88, s88, s90
	s_addc_u32 s89, s89, 0
	global_load_dword v174, v141, s[88:89] nt
	s_add_u32 s88, s88, s90
	s_addc_u32 s89, s89, 0
	global_load_dword v175, v141, s[88:89] nt
	s_add_u32 s88, s88, s90
	s_addc_u32 s89, s89, 0
	global_load_dword v176, v141, s[88:89] nt
	s_add_u32 s88, s88, s90
	s_addc_u32 s89, s89, 0
	global_load_dword v177, v141, s[88:89] nt
	s_add_u32 s88, s88, s90
	s_addc_u32 s89, s89, 0
	global_load_dword v178, v141, s[88:89] nt
	s_add_u32 s88, s88, s90
	s_addc_u32 s89, s89, 0
	global_load_dword v179, v141, s[88:89] nt
	s_add_u32 s88, s88, s90
	s_addc_u32 s89, s89, 0
	global_load_dword v180, v141, s[88:89] nt
	s_add_u32 s88, s88, s90
	s_addc_u32 s89, s89, 0
	global_load_dword v181, v141, s[88:89] nt
	s_mov_b64 exec, -1
.Lp0_nold:
	s_waitcnt lgkmcnt(0)
	ds_read2_b32 v[66:67], v103 offset1:33
	ds_read2_b32 v[68:69], v103 offset0:66 offset1:99
	ds_read2_b32 v[70:71], v103 offset0:132 offset1:165
	ds_read2_b32 v[72:73], v103 offset0:198 offset1:231
	ds_read2_b32 v[74:75], v103 offset0:8 offset1:41
	ds_read2_b32 v[76:77], v103 offset0:74 offset1:107
	ds_read2_b32 v[78:79], v103 offset0:140 offset1:173
	ds_read2_b32 v[80:81], v103 offset0:206 offset1:239
	ds_read2_b32 v[82:83], v103 offset0:16 offset1:49
	ds_read2_b32 v[84:85], v103 offset0:82 offset1:115
	ds_read2_b32 v[86:87], v103 offset0:148 offset1:181
	ds_read2_b32 v[88:89], v103 offset0:214 offset1:247
	ds_read2_b32 v[90:91], v103 offset0:24 offset1:57
	ds_read2_b32 v[94:95], v103 offset0:90 offset1:123
	ds_read2_b32 v[96:97], v103 offset0:156 offset1:189
	ds_read2_b32 v[98:99], v103 offset0:222 offset1:255
	s_waitcnt lgkmcnt(12)
	v_cvt_pk_bf16_f32 v184, v66, v67
	v_cvt_pk_bf16_f32 v185, v68, v69
	v_cvt_pk_bf16_f32 v186, v70, v71
	v_cvt_pk_bf16_f32 v187, v72, v73
	global_store_dwordx4 v108, v[184:187], s[92:93] nt
	s_waitcnt lgkmcnt(8)
	v_cvt_pk_bf16_f32 v188, v74, v75
	v_cvt_pk_bf16_f32 v189, v76, v77
	v_cvt_pk_bf16_f32 v190, v78, v79
	v_cvt_pk_bf16_f32 v191, v80, v81
	global_store_dwordx4 v109, v[188:191], s[92:93] nt
	s_waitcnt lgkmcnt(4)
	v_cvt_pk_bf16_f32 v192, v82, v83
	v_cvt_pk_bf16_f32 v193, v84, v85
	v_cvt_pk_bf16_f32 v194, v86, v87
	v_cvt_pk_bf16_f32 v195, v88, v89
	s_cmp_eq_u32 s94, 1
	s_cbranch_scc1 .Lp0_nost2
	global_store_dwordx4 v110, v[192:195], s[92:93] nt
.Lp0_nost2:
	s_waitcnt lgkmcnt(0)
	v_cvt_pk_bf16_f32 v196, v90, v91
	v_cvt_pk_bf16_f32 v197, v94, v95
	v_cvt_pk_bf16_f32 v198, v96, v97
	v_cvt_pk_bf16_f32 v199, v98, v99
	s_cmp_eq_u32 s94, 1
	s_cbranch_scc1 .Lp0_nost3
	global_store_dwordx4 v140, v[196:199], s[92:93] nt
